# grid barrier: the acquire-side L1 invalidate issued by wave 0 at barrier entry (overlapping arrive + wait) instead of after the release is observed
# speedup vs baseline: 1.0080x; 1.0055x over previous
; __device__ __forceinline__ unsigned lane_id_fresh() { unsigned m = ~0u; asm volatile("" : "+s"(m)); return __builtin_amdgcn_mbcnt_hi(m, __builtin_amdgcn_mbcnt_lo(m, 0u)); }
;     __device__ __forceinline__ const char* b(const Unit& u) const { return (const char*)Bt + (size_t)u.pn * 2 * hB() + (size_t)(u.pm >> gshift) * goff; }
;     __device__ __forceinline__ const char* b(const Unit& u) const { return (const char*)Bt + (size_t)((u.pn >> 4) * 4096 + (u.pn & 15) * 16) * 1024 * 2 + (size_t)(u.pm >> 1) * 512; }
;     __device__ __forceinline__ const char* b(const Unit& u) const { return (const char*)Bt + ((size_t)(((u.pm >> 4) * 1024 + u.pn * 256) * 16 + (u.pm & 15)) * 512) * 2; }
; __device__ __forceinline__ unsigned xb_ld(unsigned* p)              { return __hip_atomic_load(p, __ATOMIC_RELAXED, __HIP_MEMORY_SCOPE_AGENT); }
; __device__ __forceinline__ void xcd_barrier_complete(unsigned* bar, unsigned x, unsigned& nloc, unsigned& nx) {
;     const unsigned G = gridDim.x * gridDim.y * gridDim.z;
;     unsigned sum, cnt, mine, sp = 0u;
;     for (;;) {
;         sum = 0u; cnt = 0u; mine = 0u;
; #pragma unroll
;         for (unsigned j = 0; j < 16; ++j) { const unsigned c = xb_ld(&bar[XB_XCNT(j)]); sum += c; cnt += (c > 0u) ? 1u : 0u; mine = (j == x) ? c : mine; }
; __device__ __forceinline__ void xcd_barrier(const XcdBarrier& b, const int wave) {
;     asm volatile("s_waitcnt vmcnt(0)" ::: "memory");
;     __syncthreads();
;     if (wave == 0 && lane_id_fresh() == 0u) {
;         unsigned* bar = b.bar;
;         __builtin_amdgcn_s_waitcnt(0);
;         unsigned nloc = b.st[0], nx = b.st[1];
;         if (nloc == 0u) { xcd_barrier_complete(bar, b.x, nloc, nx); b.st[0] = nloc; b.st[1] = nx; }
.LBB0_109:
	s_waitcnt vmcnt(0)
	s_cmp_lt_u32 s48, 64
	s_cselect_b64 s[0:1], -1, 0
	s_cmp_gt_u32 s48, 63
	s_waitcnt lgkmcnt(0)
	s_barrier
	s_cbranch_scc1 .LBB0_163
	buffer_inv sc1
	s_mov_b32 s4, -1
	s_nop 0
	v_mbcnt_lo_u32_b32 v0, s4, 0
	v_mbcnt_hi_u32_b32 v0, s4, v0
	v_cmp_eq_u32_e32 vcc, 0, v0
	s_and_saveexec_b64 s[4:5], vcc
	s_cbranch_execz .LBB0_162
	s_add_i32 s6, 0, 0x20160
	v_mov_b32_e32 v0, s6
	s_waitcnt vmcnt(0) expcnt(0) lgkmcnt(0)
	ds_read_b32 v2, v0
	s_add_i32 s6, 0, 0x20164
	v_mov_b32_e32 v0, s6
	ds_read_b32 v0, v0
	s_waitcnt lgkmcnt(1)
	v_cmp_ne_u32_e32 vcc, 0, v2
	s_cbranch_vccnz .LBB0_126
	v_readlane_b32 s6, v254, 0
	v_readlane_b32 s7, v254, 1
	s_load_dwordx2 s[10:11], s[6:7], 0x4
	s_add_u32 s6, s94, 0x4200
	s_addc_u32 s7, s95, 0
	s_add_u32 s8, s94, 0x4400
	s_addc_u32 s9, s95, 0
	s_waitcnt lgkmcnt(0)
	s_mul_i32 s14, s10, s3
	s_add_u32 s10, s94, 0x4500
	s_mul_i32 s14, s14, s11
	s_addc_u32 s11, s95, 0
	s_add_u32 s12, s94, 0x4600
	s_addc_u32 s13, s95, 0
	s_add_u32 s16, s94, 0x4700
	s_addc_u32 s17, s95, 0
	s_add_u32 s18, s94, 0x4800
	s_addc_u32 s19, s95, 0
	s_add_u32 s20, s94, 0x4900
	s_addc_u32 s21, s95, 0
	s_add_u32 s22, s94, 0x4a00
	s_addc_u32 s23, s95, 0
	s_add_u32 s26, s94, 0x4b00
	s_addc_u32 s27, s95, 0
	s_add_u32 s28, s94, 0x4c00
	s_addc_u32 s29, s95, 0
	s_add_u32 s30, s94, 0x4d00
	s_addc_u32 s31, s95, 0
	s_add_u32 s34, s94, 0x4e00
	s_addc_u32 s35, s95, 0
	s_add_u32 s36, s94, 0x4f00
	s_addc_u32 s37, s95, 0
	s_add_u32 s40, s94, 0x5000
	s_addc_u32 s41, s95, 0
	s_add_u32 s42, s94, 0x5100
	s_addc_u32 s43, s95, 0
	s_add_u32 s44, s94, 0x5200
	s_addc_u32 s45, s95, 0
	s_add_u32 s46, s94, 0x5300
	s_addc_u32 s47, s95, 0
	s_mov_b32 s15, 1
	v_mov_b32_e32 v16, 0
	s_branch .LBB0_114

;     __device__ __forceinline__ const char* b(const Unit& u) const { return (const char*)Bt + (size_t)u.pn * 2 * hB() + (size_t)(u.pm >> gshift) * goff; }
;     __device__ __forceinline__ const char* b(const Unit& u) const { return (const char*)Bt + (size_t)((u.pn >> 4) * 4096 + (u.pn & 15) * 16) * 1024 * 2 + (size_t)(u.pm >> 1) * 512; }
;     __device__ __forceinline__ const char* b(const Unit& u) const { return (const char*)Bt + ((size_t)(((u.pm >> 4) * 1024 + u.pn * 256) * 16 + (u.pm & 15)) * 512) * 2; }
; __device__ __forceinline__ unsigned xb_ld(unsigned* p)              { return __hip_atomic_load(p, __ATOMIC_RELAXED, __HIP_MEMORY_SCOPE_AGENT); }
; #define XB_SPIN(cond, bar) do { unsigned _sp = 0; while (cond) { __builtin_amdgcn_s_sleep(1); \
;     if ((++_sp & 255u) == 0u) { if (xb_ld(&(bar)[XB_TMO])) break; if (_sp > XB_SPIN_CAP) { atomicAdd(&(bar)[XB_TMO], 1u); break; } } } } while (0)
; __device__ __forceinline__ void xcd_barrier(const XcdBarrier& b, const int wave) {
;     ...
;             XB_SPIN(xb_ld(&bar[XB_XGEN(b.x)]) == gen, bar);
;             __builtin_amdgcn_fence(__ATOMIC_ACQUIRE, "agent");
;             asm volatile("s_waitcnt vmcnt(0)" ::: "memory");
.LBB0_141:
	s_or_b64 exec, exec, s[10:11]
	s_waitcnt vmcnt(0)
	s_waitcnt vmcnt(0)

;     __device__ __forceinline__ const char* b(const Unit& u) const { return (const char*)Bt + (size_t)u.pn * 2 * hB() + (size_t)(u.pm >> gshift) * goff; }
;     __device__ __forceinline__ const char* b(const Unit& u) const { return (const char*)Bt + (size_t)((u.pn >> 4) * 4096 + (u.pn & 15) * 16) * 1024 * 2 + (size_t)(u.pm >> 1) * 512; }
;     __device__ __forceinline__ const char* b(const Unit& u) const { return (const char*)Bt + ((size_t)(((u.pm >> 4) * 1024 + u.pn * 256) * 16 + (u.pm & 15)) * 512) * 2; }
; __device__ __forceinline__ unsigned xb_ld(unsigned* p)              { return __hip_atomic_load(p, __ATOMIC_RELAXED, __HIP_MEMORY_SCOPE_AGENT); }
; __device__ __forceinline__ unsigned xb_add(unsigned* p, unsigned v) { return __hip_atomic_fetch_add(p, v, __ATOMIC_RELAXED, __HIP_MEMORY_SCOPE_AGENT); }
; #define XB_SPIN(cond, bar) do { unsigned _sp = 0; while (cond) { __builtin_amdgcn_s_sleep(1); \
;     if ((++_sp & 255u) == 0u) { if (xb_ld(&(bar)[XB_TMO])) break; if (_sp > XB_SPIN_CAP) { atomicAdd(&(bar)[XB_TMO], 1u); break; } } } } while (0)
; __device__ __forceinline__ void xcd_barrier(const XcdBarrier& b, const int wave) {
;     ...
;             if (og + 1u == (tg + 1u) * nx) xb_add(&bar[XB_TOPGEN], 1u);
;             else XB_SPIN(xb_ld(&bar[XB_TOPGEN]) == tg, bar);
;             __builtin_amdgcn_fence(__ATOMIC_ACQUIRE, "agent");
;             xb_add(&bar[XB_XGEN(b.x)], 1u);
;             asm volatile("s_waitcnt vmcnt(0)" ::: "memory");
.LBB0_159:
	s_or_b64 exec, exec, s[8:9]
	s_mov_b64 s[8:9], exec
	v_mbcnt_lo_u32_b32 v0, s8, 0
	v_mbcnt_hi_u32_b32 v0, s9, v0
	v_cmp_eq_u32_e32 vcc, 0, v0
	s_waitcnt vmcnt(0)
	s_and_saveexec_b64 s[10:11], vcc
	s_cbranch_execz .LBB0_161
	s_bcnt1_i32_b64 s8, s[8:9]
	v_mov_b32_e32 v0, 0x2000
	v_mov_b32_e32 v1, s8

; __device__ __forceinline__ unsigned lane_id_fresh() { unsigned m = ~0u; asm volatile("" : "+s"(m)); return __builtin_amdgcn_mbcnt_hi(m, __builtin_amdgcn_mbcnt_lo(m, 0u)); }
;     __device__ __forceinline__ const char* b(const Unit& u) const { return (const char*)Bt + (size_t)u.pn * 2 * hB() + (size_t)(u.pm >> gshift) * goff; }
;     __device__ __forceinline__ const char* b(const Unit& u) const { return (const char*)Bt + (size_t)((u.pn >> 4) * 4096 + (u.pn & 15) * 16) * 1024 * 2 + (size_t)(u.pm >> 1) * 512; }
;     __device__ __forceinline__ const char* b(const Unit& u) const { return (const char*)Bt + ((size_t)(((u.pm >> 4) * 1024 + u.pn * 256) * 16 + (u.pm & 15)) * 512) * 2; }
; __device__ __forceinline__ unsigned xb_ld(unsigned* p)              { return __hip_atomic_load(p, __ATOMIC_RELAXED, __HIP_MEMORY_SCOPE_AGENT); }
; __device__ __forceinline__ void xcd_barrier_complete(unsigned* bar, unsigned x, unsigned& nloc, unsigned& nx) {
;     const unsigned G = gridDim.x * gridDim.y * gridDim.z;
;     unsigned sum, cnt, mine, sp = 0u;
;     for (;;) {
;         sum = 0u; cnt = 0u; mine = 0u;
; #pragma unroll
;         for (unsigned j = 0; j < 16; ++j) { const unsigned c = xb_ld(&bar[XB_XCNT(j)]); sum += c; cnt += (c > 0u) ? 1u : 0u; mine = (j == x) ? c : mine; }
; __device__ __forceinline__ void xcd_barrier(const XcdBarrier& b, const int wave) {
;     asm volatile("s_waitcnt vmcnt(0)" ::: "memory");
;     __syncthreads();
;     if (wave == 0 && lane_id_fresh() == 0u) {
;         unsigned* bar = b.bar;
;         __builtin_amdgcn_s_waitcnt(0);
;         unsigned nloc = b.st[0], nx = b.st[1];
;         if (nloc == 0u) { xcd_barrier_complete(bar, b.x, nloc, nx); b.st[0] = nloc; b.st[1] = nx; }
.LBB0_285:
	v_cndmask_b32_e64 v0, 0, 1, s[0:1]
	s_waitcnt vmcnt(0)
	v_cmp_ne_u32_e64 s[4:5], 1, v0
	s_andn2_b64 vcc, exec, s[0:1]
	s_nop 0
	v_writelane_b32 v254, s4, 24
	s_barrier
	s_nop 0
	v_writelane_b32 v254, s5, 25
	s_cbranch_vccnz .LBB0_339
	buffer_inv sc1
	s_mov_b32 s0, -1
	s_nop 0
	v_mbcnt_lo_u32_b32 v0, s0, 0
	v_mbcnt_hi_u32_b32 v0, s0, v0
	v_cmp_eq_u32_e32 vcc, 0, v0
	s_and_saveexec_b64 s[0:1], vcc
	s_cbranch_execz .LBB0_338
	s_add_i32 s4, 0, 0x20160
	v_mov_b32_e32 v0, s4
	s_waitcnt vmcnt(0) expcnt(0) lgkmcnt(0)
	ds_read_b32 v2, v0
	s_add_i32 s4, 0, 0x20164
	v_mov_b32_e32 v0, s4
	ds_read_b32 v0, v0
	s_waitcnt lgkmcnt(1)
	v_cmp_ne_u32_e32 vcc, 0, v2
	s_cbranch_vccnz .LBB0_302
	v_readlane_b32 s4, v254, 0
	v_readlane_b32 s5, v254, 1
	s_load_dwordx2 s[8:9], s[4:5], 0x4
	s_add_u32 s4, s94, 0x4200
	s_addc_u32 s5, s95, 0
	s_add_u32 s6, s94, 0x4400
	s_addc_u32 s7, s95, 0
	s_waitcnt lgkmcnt(0)
	s_mul_i32 s14, s8, s3
	s_add_u32 s8, s94, 0x4500
	s_mul_i32 s14, s14, s9
	s_addc_u32 s9, s95, 0
	s_add_u32 s10, s94, 0x4600
	s_addc_u32 s11, s95, 0
	s_add_u32 s12, s94, 0x4700
	s_addc_u32 s13, s95, 0
	s_add_u32 s16, s94, 0x4800
	s_addc_u32 s17, s95, 0
	s_add_u32 s18, s94, 0x4900
	s_addc_u32 s19, s95, 0
	s_add_u32 s20, s94, 0x4a00
	s_addc_u32 s21, s95, 0
	s_add_u32 s22, s94, 0x4b00
	s_addc_u32 s23, s95, 0
	s_add_u32 s24, s94, 0x4c00
	s_addc_u32 s25, s95, 0
	s_add_u32 s26, s94, 0x4d00
	s_addc_u32 s27, s95, 0
	s_add_u32 s28, s94, 0x4e00
	s_addc_u32 s29, s95, 0
	s_add_u32 s30, s94, 0x4f00
	s_addc_u32 s31, s95, 0
	s_add_u32 s34, s94, 0x5000
	s_addc_u32 s35, s95, 0
	s_add_u32 s36, s94, 0x5100
	s_addc_u32 s37, s95, 0
	s_add_u32 s40, s94, 0x5200
	s_addc_u32 s41, s95, 0
	s_add_u32 s42, s94, 0x5300
	s_addc_u32 s43, s95, 0
	s_mov_b32 s15, 1
	v_mov_b32_e32 v16, 0
	s_branch .LBB0_290

;     __device__ __forceinline__ const char* b(const Unit& u) const { return (const char*)Bt + (size_t)u.pn * 2 * hB() + (size_t)(u.pm >> gshift) * goff; }
;     __device__ __forceinline__ const char* b(const Unit& u) const { return (const char*)Bt + (size_t)((u.pn >> 4) * 4096 + (u.pn & 15) * 16) * 1024 * 2 + (size_t)(u.pm >> 1) * 512; }
;     __device__ __forceinline__ const char* b(const Unit& u) const { return (const char*)Bt + ((size_t)(((u.pm >> 4) * 1024 + u.pn * 256) * 16 + (u.pm & 15)) * 512) * 2; }
; __device__ __forceinline__ unsigned xb_ld(unsigned* p)              { return __hip_atomic_load(p, __ATOMIC_RELAXED, __HIP_MEMORY_SCOPE_AGENT); }
; #define XB_SPIN(cond, bar) do { unsigned _sp = 0; while (cond) { __builtin_amdgcn_s_sleep(1); \
;     if ((++_sp & 255u) == 0u) { if (xb_ld(&(bar)[XB_TMO])) break; if (_sp > XB_SPIN_CAP) { atomicAdd(&(bar)[XB_TMO], 1u); break; } } } } while (0)
; __device__ __forceinline__ void xcd_barrier(const XcdBarrier& b, const int wave) {
;     ...
;             XB_SPIN(xb_ld(&bar[XB_XGEN(b.x)]) == gen, bar);
;             __builtin_amdgcn_fence(__ATOMIC_ACQUIRE, "agent");
;             asm volatile("s_waitcnt vmcnt(0)" ::: "memory");
.LBB0_317:
	s_or_b64 exec, exec, s[8:9]
	s_waitcnt vmcnt(0)
	s_waitcnt vmcnt(0)

;     __device__ __forceinline__ const char* b(const Unit& u) const { return (const char*)Bt + (size_t)u.pn * 2 * hB() + (size_t)(u.pm >> gshift) * goff; }
;     __device__ __forceinline__ const char* b(const Unit& u) const { return (const char*)Bt + (size_t)((u.pn >> 4) * 4096 + (u.pn & 15) * 16) * 1024 * 2 + (size_t)(u.pm >> 1) * 512; }
;     __device__ __forceinline__ const char* b(const Unit& u) const { return (const char*)Bt + ((size_t)(((u.pm >> 4) * 1024 + u.pn * 256) * 16 + (u.pm & 15)) * 512) * 2; }
; __device__ __forceinline__ unsigned xb_ld(unsigned* p)              { return __hip_atomic_load(p, __ATOMIC_RELAXED, __HIP_MEMORY_SCOPE_AGENT); }
; __device__ __forceinline__ unsigned xb_add(unsigned* p, unsigned v) { return __hip_atomic_fetch_add(p, v, __ATOMIC_RELAXED, __HIP_MEMORY_SCOPE_AGENT); }
; #define XB_SPIN(cond, bar) do { unsigned _sp = 0; while (cond) { __builtin_amdgcn_s_sleep(1); \
;     if ((++_sp & 255u) == 0u) { if (xb_ld(&(bar)[XB_TMO])) break; if (_sp > XB_SPIN_CAP) { atomicAdd(&(bar)[XB_TMO], 1u); break; } } } } while (0)
; __device__ __forceinline__ void xcd_barrier(const XcdBarrier& b, const int wave) {
;     ...
;             if (og + 1u == (tg + 1u) * nx) xb_add(&bar[XB_TOPGEN], 1u);
;             else XB_SPIN(xb_ld(&bar[XB_TOPGEN]) == tg, bar);
;             __builtin_amdgcn_fence(__ATOMIC_ACQUIRE, "agent");
;             xb_add(&bar[XB_XGEN(b.x)], 1u);
;             asm volatile("s_waitcnt vmcnt(0)" ::: "memory");
.LBB0_335:
	s_or_b64 exec, exec, s[6:7]
	s_mov_b64 s[6:7], exec
	v_mbcnt_lo_u32_b32 v0, s6, 0
	v_mbcnt_hi_u32_b32 v0, s7, v0
	v_cmp_eq_u32_e32 vcc, 0, v0
	s_waitcnt vmcnt(0)
	s_and_saveexec_b64 s[8:9], vcc
	s_cbranch_execz .LBB0_337
	s_bcnt1_i32_b64 s6, s[6:7]
	v_mov_b32_e32 v0, 0x2000
	v_mov_b32_e32 v1, s6

; __device__ __forceinline__ unsigned lane_id_fresh() { unsigned m = ~0u; asm volatile("" : "+s"(m)); return __builtin_amdgcn_mbcnt_hi(m, __builtin_amdgcn_mbcnt_lo(m, 0u)); }
;     __device__ __forceinline__ const char* b(const Unit& u) const { return (const char*)Bt + (size_t)u.pn * 2 * hB() + (size_t)(u.pm >> gshift) * goff; }
;     __device__ __forceinline__ const char* b(const Unit& u) const { return (const char*)Bt + (size_t)((u.pn >> 4) * 4096 + (u.pn & 15) * 16) * 1024 * 2 + (size_t)(u.pm >> 1) * 512; }
;     __device__ __forceinline__ const char* b(const Unit& u) const { return (const char*)Bt + ((size_t)(((u.pm >> 4) * 1024 + u.pn * 256) * 16 + (u.pm & 15)) * 512) * 2; }
; __device__ __forceinline__ unsigned xb_ld(unsigned* p)              { return __hip_atomic_load(p, __ATOMIC_RELAXED, __HIP_MEMORY_SCOPE_AGENT); }
; __device__ __forceinline__ void xcd_barrier_complete(unsigned* bar, unsigned x, unsigned& nloc, unsigned& nx) {
;     const unsigned G = gridDim.x * gridDim.y * gridDim.z;
;     unsigned sum, cnt, mine, sp = 0u;
;     for (;;) {
;         sum = 0u; cnt = 0u; mine = 0u;
; #pragma unroll
;         for (unsigned j = 0; j < 16; ++j) { const unsigned c = xb_ld(&bar[XB_XCNT(j)]); sum += c; cnt += (c > 0u) ? 1u : 0u; mine = (j == x) ? c : mine; }
; __device__ __forceinline__ void xcd_barrier(const XcdBarrier& b, const int wave) {
;     asm volatile("s_waitcnt vmcnt(0)" ::: "memory");
;     __syncthreads();
;     if (wave == 0 && lane_id_fresh() == 0u) {
;         unsigned* bar = b.bar;
;         __builtin_amdgcn_s_waitcnt(0);
;         unsigned nloc = b.st[0], nx = b.st[1];
;         if (nloc == 0u) { xcd_barrier_complete(bar, b.x, nloc, nx); b.st[0] = nloc; b.st[1] = nx; }
.LBB0_417:
	s_waitcnt vmcnt(0)
	v_readlane_b32 s4, v254, 24
	v_readlane_b32 s5, v254, 25
	s_and_b64 vcc, exec, s[4:5]
	s_waitcnt vmcnt(0) lgkmcnt(0)
	s_barrier
	s_cbranch_vccnz .LBB0_471
	buffer_inv sc1
	s_mov_b32 s4, -1
	s_nop 0
	v_mbcnt_lo_u32_b32 v0, s4, 0
	v_mbcnt_hi_u32_b32 v0, s4, v0
	v_cmp_eq_u32_e32 vcc, 0, v0
	s_and_saveexec_b64 s[4:5], vcc
	s_cbranch_execz .LBB0_470
	s_add_i32 s6, 0, 0x20160
	v_mov_b32_e32 v0, s6
	s_waitcnt vmcnt(0) expcnt(0) lgkmcnt(0)
	ds_read_b32 v2, v0
	s_add_i32 s6, 0, 0x20164
	v_mov_b32_e32 v0, s6
	ds_read_b32 v0, v0
	s_waitcnt lgkmcnt(1)
	v_cmp_ne_u32_e32 vcc, 0, v2
	s_cbranch_vccnz .LBB0_434
	v_readlane_b32 s6, v254, 0
	v_readlane_b32 s7, v254, 1
	s_load_dwordx2 s[10:11], s[6:7], 0x4
	s_add_u32 s6, s94, 0x4200
	s_addc_u32 s7, s95, 0
	s_add_u32 s8, s94, 0x4400
	s_addc_u32 s9, s95, 0
	s_waitcnt lgkmcnt(0)
	s_mul_i32 s14, s10, s3
	s_add_u32 s10, s94, 0x4500
	s_mul_i32 s14, s14, s11
	s_addc_u32 s11, s95, 0
	s_add_u32 s12, s94, 0x4600
	s_addc_u32 s13, s95, 0
	s_add_u32 s16, s94, 0x4700
	s_addc_u32 s17, s95, 0
	s_add_u32 s18, s94, 0x4800
	s_addc_u32 s19, s95, 0
	s_add_u32 s20, s94, 0x4900
	s_addc_u32 s21, s95, 0
	s_add_u32 s22, s94, 0x4a00
	s_addc_u32 s23, s95, 0
	s_add_u32 s24, s94, 0x4b00
	s_addc_u32 s25, s95, 0
	s_add_u32 s26, s94, 0x4c00
	s_addc_u32 s27, s95, 0
	s_add_u32 s28, s94, 0x4d00
	s_addc_u32 s29, s95, 0
	s_add_u32 s30, s94, 0x4e00
	s_addc_u32 s31, s95, 0
	s_add_u32 s34, s94, 0x4f00
	s_addc_u32 s35, s95, 0
	s_add_u32 s36, s94, 0x5000
	s_addc_u32 s37, s95, 0
	s_add_u32 s40, s94, 0x5100
	s_addc_u32 s41, s95, 0
	s_add_u32 s42, s94, 0x5200
	s_addc_u32 s43, s95, 0
	s_add_u32 s44, s94, 0x5300
	s_addc_u32 s45, s95, 0
	s_mov_b32 s15, 1
	v_mov_b32_e32 v16, 0
	s_branch .LBB0_422

; __device__ __forceinline__ unsigned lane_id_fresh() { unsigned m = ~0u; asm volatile("" : "+s"(m)); return __builtin_amdgcn_mbcnt_hi(m, __builtin_amdgcn_mbcnt_lo(m, 0u)); }
;     __device__ __forceinline__ const char* b(const Unit& u) const { return (const char*)Bt + (size_t)u.pn * 2 * hB() + (size_t)(u.pm >> gshift) * goff; }
;     __device__ __forceinline__ const char* b(const Unit& u) const { return (const char*)Bt + (size_t)((u.pn >> 4) * 4096 + (u.pn & 15) * 16) * 1024 * 2 + (size_t)(u.pm >> 1) * 512; }
;     __device__ __forceinline__ const char* b(const Unit& u) const { return (const char*)Bt + ((size_t)(((u.pm >> 4) * 1024 + u.pn * 256) * 16 + (u.pm & 15)) * 512) * 2; }
; __device__ __forceinline__ unsigned xb_ld(unsigned* p)              { return __hip_atomic_load(p, __ATOMIC_RELAXED, __HIP_MEMORY_SCOPE_AGENT); }
; __device__ __forceinline__ void xcd_barrier_complete(unsigned* bar, unsigned x, unsigned& nloc, unsigned& nx) {
;     const unsigned G = gridDim.x * gridDim.y * gridDim.z;
;     unsigned sum, cnt, mine, sp = 0u;
;     for (;;) {
;         sum = 0u; cnt = 0u; mine = 0u;
; #pragma unroll
;         for (unsigned j = 0; j < 16; ++j) { const unsigned c = xb_ld(&bar[XB_XCNT(j)]); sum += c; cnt += (c > 0u) ? 1u : 0u; mine = (j == x) ? c : mine; }
; __device__ __forceinline__ void xcd_barrier(const XcdBarrier& b, const int wave) {
;     asm volatile("s_waitcnt vmcnt(0)" ::: "memory");
;     __syncthreads();
;     if (wave == 0 && lane_id_fresh() == 0u) {
;         unsigned* bar = b.bar;
;         __builtin_amdgcn_s_waitcnt(0);
;         unsigned nloc = b.st[0], nx = b.st[1];
;         if (nloc == 0u) { xcd_barrier_complete(bar, b.x, nloc, nx); b.st[0] = nloc; b.st[1] = nx; }
.LBB0_544:
	s_waitcnt vmcnt(0)
	v_readlane_b32 s0, v254, 24
	v_readlane_b32 s1, v254, 25
	s_and_b64 vcc, exec, s[0:1]
	s_waitcnt vmcnt(0)
	s_barrier
	s_cbranch_vccnz .LBB0_598
	buffer_inv sc1
	s_mov_b32 s0, -1
	s_nop 0
	v_mbcnt_lo_u32_b32 v0, s0, 0
	v_mbcnt_hi_u32_b32 v0, s0, v0
	v_cmp_eq_u32_e32 vcc, 0, v0
	s_and_saveexec_b64 s[0:1], vcc
	s_cbranch_execz .LBB0_597
	s_add_i32 s4, 0, 0x20160
	v_mov_b32_e32 v0, s4
	s_waitcnt vmcnt(0) expcnt(0) lgkmcnt(0)
	ds_read_b32 v2, v0
	s_add_i32 s4, 0, 0x20164
	v_mov_b32_e32 v0, s4
	ds_read_b32 v0, v0
	s_waitcnt lgkmcnt(1)
	v_cmp_ne_u32_e32 vcc, 0, v2
	s_cbranch_vccnz .LBB0_561
	v_readlane_b32 s4, v254, 0
	v_readlane_b32 s5, v254, 1
	s_load_dwordx2 s[8:9], s[4:5], 0x4
	s_add_u32 s4, s94, 0x4200
	s_addc_u32 s5, s95, 0
	s_add_u32 s6, s94, 0x4400
	s_addc_u32 s7, s95, 0
	s_waitcnt lgkmcnt(0)
	s_mul_i32 s14, s8, s3
	s_add_u32 s8, s94, 0x4500
	s_mul_i32 s14, s14, s9
	s_addc_u32 s9, s95, 0
	s_add_u32 s10, s94, 0x4600
	s_addc_u32 s11, s95, 0
	s_add_u32 s12, s94, 0x4700
	s_addc_u32 s13, s95, 0
	s_add_u32 s16, s94, 0x4800
	s_addc_u32 s17, s95, 0
	s_add_u32 s18, s94, 0x4900
	s_addc_u32 s19, s95, 0
	s_add_u32 s20, s94, 0x4a00
	s_addc_u32 s21, s95, 0
	s_add_u32 s22, s94, 0x4b00
	s_addc_u32 s23, s95, 0
	s_add_u32 s24, s94, 0x4c00
	s_addc_u32 s25, s95, 0
	s_add_u32 s26, s94, 0x4d00
	s_addc_u32 s27, s95, 0
	s_add_u32 s28, s94, 0x4e00
	s_addc_u32 s29, s95, 0
	s_add_u32 s30, s94, 0x4f00
	s_addc_u32 s31, s95, 0
	s_add_u32 s34, s94, 0x5000
	s_addc_u32 s35, s95, 0
	s_add_u32 s36, s94, 0x5100
	s_addc_u32 s37, s95, 0
	s_add_u32 s40, s94, 0x5200
	s_addc_u32 s41, s95, 0
	s_add_u32 s42, s94, 0x5300
	s_addc_u32 s43, s95, 0
	s_mov_b32 s15, 1
	v_mov_b32_e32 v16, 0
	s_branch .LBB0_549

; __device__ __forceinline__ unsigned lane_id_fresh() { unsigned m = ~0u; asm volatile("" : "+s"(m)); return __builtin_amdgcn_mbcnt_hi(m, __builtin_amdgcn_mbcnt_lo(m, 0u)); }
;     __device__ __forceinline__ const char* b(const Unit& u) const { return (const char*)Bt + (size_t)u.pn * 2 * hB() + (size_t)(u.pm >> gshift) * goff; }
;     __device__ __forceinline__ const char* b(const Unit& u) const { return (const char*)Bt + (size_t)((u.pn >> 4) * 4096 + (u.pn & 15) * 16) * 1024 * 2 + (size_t)(u.pm >> 1) * 512; }
;     __device__ __forceinline__ const char* b(const Unit& u) const { return (const char*)Bt + ((size_t)(((u.pm >> 4) * 1024 + u.pn * 256) * 16 + (u.pm & 15)) * 512) * 2; }
; __device__ __forceinline__ unsigned xb_ld(unsigned* p)              { return __hip_atomic_load(p, __ATOMIC_RELAXED, __HIP_MEMORY_SCOPE_AGENT); }
; __device__ __forceinline__ void xcd_barrier_complete(unsigned* bar, unsigned x, unsigned& nloc, unsigned& nx) {
;     const unsigned G = gridDim.x * gridDim.y * gridDim.z;
;     unsigned sum, cnt, mine, sp = 0u;
;     for (;;) {
;         sum = 0u; cnt = 0u; mine = 0u;
; #pragma unroll
;         for (unsigned j = 0; j < 16; ++j) { const unsigned c = xb_ld(&bar[XB_XCNT(j)]); sum += c; cnt += (c > 0u) ? 1u : 0u; mine = (j == x) ? c : mine; }
; __device__ __forceinline__ void xcd_barrier(const XcdBarrier& b, const int wave) {
;     asm volatile("s_waitcnt vmcnt(0)" ::: "memory");
;     __syncthreads();
;     if (wave == 0 && lane_id_fresh() == 0u) {
;         unsigned* bar = b.bar;
;         __builtin_amdgcn_s_waitcnt(0);
;         unsigned nloc = b.st[0], nx = b.st[1];
;         if (nloc == 0u) { xcd_barrier_complete(bar, b.x, nloc, nx); b.st[0] = nloc; b.st[1] = nx; }
.LBB0_646:
	s_waitcnt vmcnt(0)
	v_readlane_b32 s0, v254, 24
	v_readlane_b32 s1, v254, 25
	s_and_b64 vcc, exec, s[0:1]
	s_waitcnt lgkmcnt(0)
	s_barrier
	s_cbranch_vccnz .LBB0_700
	buffer_inv sc1
	s_mov_b32 s0, -1
	s_nop 0
	v_mbcnt_lo_u32_b32 v0, s0, 0
	v_mbcnt_hi_u32_b32 v0, s0, v0
	v_cmp_eq_u32_e32 vcc, 0, v0
	s_and_saveexec_b64 s[0:1], vcc
	s_cbranch_execz .LBB0_699
	s_add_i32 s4, 0, 0x20160
	v_mov_b32_e32 v0, s4
	s_waitcnt vmcnt(0) expcnt(0) lgkmcnt(0)
	ds_read_b32 v2, v0
	s_add_i32 s4, 0, 0x20164
	v_mov_b32_e32 v0, s4
	ds_read_b32 v0, v0
	s_waitcnt lgkmcnt(1)
	v_cmp_ne_u32_e32 vcc, 0, v2
	s_cbranch_vccnz .LBB0_663
	v_readlane_b32 s4, v254, 0
	v_readlane_b32 s5, v254, 1
	s_load_dwordx2 s[8:9], s[4:5], 0x4
	s_add_u32 s4, s94, 0x4200
	s_addc_u32 s5, s95, 0
	s_add_u32 s6, s94, 0x4400
	s_addc_u32 s7, s95, 0
	s_waitcnt lgkmcnt(0)
	s_mul_i32 s38, s8, s3
	s_add_u32 s8, s94, 0x4500
	s_mul_i32 s38, s38, s9
	s_addc_u32 s9, s95, 0
	s_add_u32 s10, s94, 0x4600
	s_addc_u32 s11, s95, 0
	s_add_u32 s12, s94, 0x4700
	s_addc_u32 s13, s95, 0
	s_add_u32 s14, s94, 0x4800
	s_addc_u32 s15, s95, 0
	s_add_u32 s16, s94, 0x4900
	s_addc_u32 s17, s95, 0
	s_add_u32 s18, s94, 0x4a00
	s_addc_u32 s19, s95, 0
	s_add_u32 s20, s94, 0x4b00
	s_addc_u32 s21, s95, 0
	s_add_u32 s22, s94, 0x4c00
	s_addc_u32 s23, s95, 0
	s_add_u32 s24, s94, 0x4d00
	s_addc_u32 s25, s95, 0
	s_add_u32 s26, s94, 0x4e00
	s_addc_u32 s27, s95, 0
	s_add_u32 s28, s94, 0x4f00
	s_addc_u32 s29, s95, 0
	s_add_u32 s30, s94, 0x5000
	s_addc_u32 s31, s95, 0
	s_add_u32 s34, s94, 0x5100
	s_addc_u32 s35, s95, 0
	s_add_u32 s36, s94, 0x5200
	s_addc_u32 s37, s95, 0
	s_add_u32 s40, s94, 0x5300
	s_addc_u32 s41, s95, 0
	s_mov_b32 s39, 1
	v_mov_b32_e32 v16, 0
	s_branch .LBB0_651

; __device__ __forceinline__ unsigned lane_id_fresh() { unsigned m = ~0u; asm volatile("" : "+s"(m)); return __builtin_amdgcn_mbcnt_hi(m, __builtin_amdgcn_mbcnt_lo(m, 0u)); }
;     __device__ __forceinline__ const char* b(const Unit& u) const { return (const char*)Bt + (size_t)u.pn * 2 * hB() + (size_t)(u.pm >> gshift) * goff; }
;     __device__ __forceinline__ const char* b(const Unit& u) const { return (const char*)Bt + (size_t)((u.pn >> 4) * 4096 + (u.pn & 15) * 16) * 1024 * 2 + (size_t)(u.pm >> 1) * 512; }
;     __device__ __forceinline__ const char* b(const Unit& u) const { return (const char*)Bt + ((size_t)(((u.pm >> 4) * 1024 + u.pn * 256) * 16 + (u.pm & 15)) * 512) * 2; }
; __device__ __forceinline__ void xcd_barrier_complete(unsigned* bar, unsigned x, unsigned& nloc, unsigned& nx) {
;     const unsigned G = gridDim.x * gridDim.y * gridDim.z;
;     unsigned sum, cnt, mine, sp = 0u;
; __device__ __forceinline__ void xcd_barrier(const XcdBarrier& b, const int wave) {
;     asm volatile("s_waitcnt vmcnt(0)" ::: "memory");
;     __syncthreads();
;     if (wave == 0 && lane_id_fresh() == 0u) {
;         unsigned* bar = b.bar;
;         __builtin_amdgcn_s_waitcnt(0);
;         unsigned nloc = b.st[0], nx = b.st[1];
;         if (nloc == 0u) { xcd_barrier_complete(bar, b.x, nloc, nx); b.st[0] = nloc; b.st[1] = nx; }
.LBB0_723:
	s_waitcnt vmcnt(0)
	v_readlane_b32 s0, v254, 24
	v_readlane_b32 s1, v254, 25
	s_and_b64 vcc, exec, s[0:1]
	s_barrier
	s_cbranch_vccnz .LBB0_777
	buffer_inv sc1
	s_mov_b32 s0, s70
	s_nop 0
	v_mbcnt_lo_u32_b32 v0, s0, 0
	v_mbcnt_hi_u32_b32 v0, s0, v0
	v_cmp_eq_u32_e32 vcc, 0, v0
	s_and_saveexec_b64 s[20:21], vcc
	s_cbranch_execz .LBB0_776
	v_readlane_b32 s0, v255, 44
	s_waitcnt vmcnt(0) expcnt(0) lgkmcnt(0)
	s_nop 0
	v_mov_b32_e32 v0, s0
	ds_read_b32 v2, v0
	v_readlane_b32 s0, v255, 45
	s_waitcnt lgkmcnt(0)
	v_cmp_ne_u32_e32 vcc, 0, v2
	v_mov_b32_e32 v0, s0
	ds_read_b32 v0, v0
	s_cbranch_vccnz .LBB0_740
	v_readlane_b32 s22, v254, 0
	v_readlane_b32 s23, v254, 1
	s_load_dwordx2 s[0:1], s[22:23], 0x4
	s_waitcnt lgkmcnt(0)
	s_mul_i32 s0, s0, s3
	s_mul_i32 s0, s0, s1
	s_mov_b32 s1, 1
	s_branch .LBB0_728

;     __device__ __forceinline__ const char* b(const Unit& u) const { return (const char*)Bt + (size_t)u.pn * 2 * hB() + (size_t)(u.pm >> gshift) * goff; }
;     __device__ __forceinline__ const char* b(const Unit& u) const { return (const char*)Bt + (size_t)((u.pn >> 4) * 4096 + (u.pn & 15) * 16) * 1024 * 2 + (size_t)(u.pm >> 1) * 512; }
;     __device__ __forceinline__ const char* b(const Unit& u) const { return (const char*)Bt + ((size_t)(((u.pm >> 4) * 1024 + u.pn * 256) * 16 + (u.pm & 15)) * 512) * 2; }
; __device__ __forceinline__ unsigned xb_ld(unsigned* p)              { return __hip_atomic_load(p, __ATOMIC_RELAXED, __HIP_MEMORY_SCOPE_AGENT); }
; #define XB_SPIN(cond, bar) do { unsigned _sp = 0; while (cond) { __builtin_amdgcn_s_sleep(1); \
;     if ((++_sp & 255u) == 0u) { if (xb_ld(&(bar)[XB_TMO])) break; if (_sp > XB_SPIN_CAP) { atomicAdd(&(bar)[XB_TMO], 1u); break; } } } } while (0)
; __device__ __forceinline__ void xcd_barrier(const XcdBarrier& b, const int wave) {
;     ...
;             XB_SPIN(xb_ld(&bar[XB_XGEN(b.x)]) == gen, bar);
;             __builtin_amdgcn_fence(__ATOMIC_ACQUIRE, "agent");
;             asm volatile("s_waitcnt vmcnt(0)" ::: "memory");
.LBB0_755:
	s_or_b64 exec, exec, s[24:25]
	s_waitcnt vmcnt(0)
	s_waitcnt vmcnt(0)

;     __device__ __forceinline__ const char* b(const Unit& u) const { return (const char*)Bt + (size_t)u.pn * 2 * hB() + (size_t)(u.pm >> gshift) * goff; }
;     __device__ __forceinline__ const char* b(const Unit& u) const { return (const char*)Bt + (size_t)((u.pn >> 4) * 4096 + (u.pn & 15) * 16) * 1024 * 2 + (size_t)(u.pm >> 1) * 512; }
;     __device__ __forceinline__ const char* b(const Unit& u) const { return (const char*)Bt + ((size_t)(((u.pm >> 4) * 1024 + u.pn * 256) * 16 + (u.pm & 15)) * 512) * 2; }
; __device__ __forceinline__ unsigned xb_ld(unsigned* p)              { return __hip_atomic_load(p, __ATOMIC_RELAXED, __HIP_MEMORY_SCOPE_AGENT); }
; __device__ __forceinline__ unsigned xb_add(unsigned* p, unsigned v) { return __hip_atomic_fetch_add(p, v, __ATOMIC_RELAXED, __HIP_MEMORY_SCOPE_AGENT); }
; #define XB_SPIN(cond, bar) do { unsigned _sp = 0; while (cond) { __builtin_amdgcn_s_sleep(1); \
;     if ((++_sp & 255u) == 0u) { if (xb_ld(&(bar)[XB_TMO])) break; if (_sp > XB_SPIN_CAP) { atomicAdd(&(bar)[XB_TMO], 1u); break; } } } } while (0)
; __device__ __forceinline__ void xcd_barrier(const XcdBarrier& b, const int wave) {
;     ...
;             if (og + 1u == (tg + 1u) * nx) xb_add(&bar[XB_TOPGEN], 1u);
;             else XB_SPIN(xb_ld(&bar[XB_TOPGEN]) == tg, bar);
;             __builtin_amdgcn_fence(__ATOMIC_ACQUIRE, "agent");
;             xb_add(&bar[XB_XGEN(b.x)], 1u);
;             asm volatile("s_waitcnt vmcnt(0)" ::: "memory");
.LBB0_773:
	s_or_b64 exec, exec, s[22:23]
	s_mov_b64 s[22:23], exec
	v_mbcnt_lo_u32_b32 v0, s22, 0
	v_mbcnt_hi_u32_b32 v0, s23, v0
	v_cmp_eq_u32_e32 vcc, 0, v0
	s_waitcnt vmcnt(0)
	s_and_saveexec_b64 s[24:25], vcc
	s_cbranch_execz .LBB0_775
	s_bcnt1_i32_b64 s0, s[22:23]
	v_mov_b32_e32 v0, s0
	v_readlane_b32 s0, v254, 32
	v_readlane_b32 s1, v254, 33
	s_nop 4
